# P5b tail rebalanced: FFN2 w1/w3 conversion items split between HGRN workgroups (3 of 11 rounds, after their GEMM unit) and mLSTM workgroups (8 rounds, after their now-shorter scan)
# speedup vs baseline: 1.0134x; 1.0107x over previous
.LBB0_512:
	v_readlane_b32 s0, v251, 36
	v_readlane_b32 s50, v251, 47
	v_readlane_b32 s1, v251, 37
	v_readlane_b32 s51, v251, 48
	s_and_b64 s[0:1], s[50:51], s[0:1]
	v_readlane_b32 s84, v251, 42
	s_andn2_b64 vcc, exec, s[0:1]
	v_readlane_b32 s60, v251, 40
	v_readlane_b32 s62, v251, 38
	v_readlane_b32 s85, v251, 43
	v_readlane_b32 s61, v251, 41
	v_readlane_b32 s63, v251, 39
	s_cbranch_vccnz .LBB0_539
	s_movk_i32 s93, 0xc00
	s_mov_b32 s94, 0
	s_cmpk_lt_i32 s64, 0x80
	s_cbranch_scc1 .Ltail_hgrn
	s_movk_i32 s93, 0x2c00
	s_movk_i32 s94, 0x800
	s_branch .Ltail_conv
.Ltail_hgrn:
	s_ashr_i32 s26, s64, 31
	s_lshr_b32 s0, s26, 29
	s_add_i32 s5, s64, s0
	s_and_b32 s0, s5, -8
	s_sub_i32 s4, s64, s0
	s_cmp_gt_i32 s4, -1
	v_readfirstlane_b32 s2, v221
	s_waitcnt lgkmcnt(0)
	s_barrier
	s_cbranch_scc0 .LBB0_515
	s_lshl_b32 s3, s4, 4
	s_mov_b64 s[0:1], 0
	s_branch .LBB0_516

.LBB0_536:
	s_waitcnt vmcnt(0)
	s_cmpk_gt_i32 s60, 0xbff
	s_barrier
	s_waitcnt vmcnt(0)
	s_barrier
	s_cbranch_scc1 .LBB0_539
.Ltail_conv:
	v_lshlrev_b32_e32 v0, 3, v221
	v_and_b32_e32 v0, 56, v0
	v_readlane_b32 s2, v251, 4
	v_lshrrev_b32_e32 v4, 5, v220
	v_and_b32_e32 v10, 31, v221
	v_mov_b32_e32 v1, 0
	v_readlane_b32 s0, v251, 9
	v_lshrrev_b32_e32 v5, 3, v220
	v_mul_u32_u24_e32 v6, 0x84, v0
	v_lshlrev_b32_e32 v0, 1, v0
	v_readlane_b32 s3, v251, 5
	v_lshl_add_u32 v11, v10, 2, s0
	v_mul_u32_u24_e32 v12, 0x84, v4
	v_lshl_add_u64 v[2:3], s[2:3], 0, v[0:1]
	v_lshlrev_b32_e32 v0, 2, v5
	v_add3_u32 v6, s0, v6, v0
	v_lshlrev_b32_e32 v0, 2, v10
	v_add_u32_e32 v10, v11, v12
	v_or_b32_e32 v7, 8, v5
	v_or_b32_e32 v8, 16, v5
	v_or_b32_e32 v9, 24, v5
	s_movk_i32 s4, 0x5800
	v_add_u32_e32 v11, 0x400, v10
	v_add_u32_e32 v12, 0x800, v10
	v_add_u32_e32 v13, 0xc00, v10
	v_add_u32_e32 v14, 0x1000, v10
	v_add_u32_e32 v15, 0x1400, v10
	v_add_u32_e32 v16, 0x1800, v10
	v_add_u32_e32 v17, 0x1c00, v10
	s_add_i32 s5, s60, s94
.LBB0_538:
	s_add_i32 s0, s5, 0xffffea00
	s_cmpk_gt_i32 s5, 0x15ff
	s_cselect_b32 s2, s0, s5
	s_mul_hi_i32 s0, s2, 0x2e8ba2e9
	s_cselect_b32 s1, 0x80, 0
	s_cselect_b32 s8, s69, s67
	s_cselect_b32 s9, s68, s66
	s_lshr_b32 s3, s0, 31
	s_ashr_i32 s0, s0, 5
	s_add_i32 s0, s0, s3
	s_mul_i32 s3, s0, 0xb0
	s_sub_i32 s3, s2, s3
	s_lshl_b32 s2, s3, 5
	s_lshl_b32 s3, s3, 6
	s_and_b32 s6, s3, 0xffffff00
	s_and_b32 s10, s2, 0x60
	s_ashr_i32 s3, s2, 31
	s_or_b32 s1, s6, s1
	s_lshl_b32 s0, s0, 6
	s_lshl_b64 s[6:7], s[2:3], 2
	s_or_b32 s2, s1, s10
	s_add_u32 s6, s9, s6
	v_or_b32_e32 v20, s0, v4
	s_addc_u32 s7, s8, s7
	v_or_b32_e32 v30, 10, v20
	v_or_b32_e32 v32, 12, v20
	v_or_b32_e32 v34, 14, v20
	v_or_b32_e32 v36, 16, v20
	v_or_b32_e32 v38, 18, v20
	v_or_b32_e32 v40, 20, v20
	v_or_b32_e32 v42, 22, v20
	v_or_b32_e32 v44, 24, v20
	v_or_b32_e32 v46, 26, v20
	v_or_b32_e32 v48, 28, v20
	v_or_b32_e32 v50, 30, v20
	v_or_b32_e32 v52, 32, v20
	v_or_b32_e32 v54, 34, v20
	v_or_b32_e32 v56, 36, v20
	v_lshl_add_u64 v[18:19], s[6:7], 0, v[0:1]
	v_or_b32_e32 v22, 2, v20
	v_or_b32_e32 v24, 4, v20
	v_or_b32_e32 v26, 6, v20
	v_or_b32_e32 v28, 8, v20
	v_or_b32_e32 v58, 38, v20
	v_or_b32_e32 v60, 40, v20
	v_or_b32_e32 v62, 42, v20
	v_or_b32_e32 v64, 44, v20
	v_or_b32_e32 v66, 46, v20
	v_or_b32_e32 v68, 48, v20
	v_or_b32_e32 v70, 50, v20
	v_or_b32_e32 v72, 52, v20
	v_or_b32_e32 v74, 54, v20
	v_or_b32_e32 v76, 56, v20
	v_or_b32_e32 v78, 58, v20
	v_or_b32_e32 v80, 60, v20
	v_or_b32_e32 v82, 62, v20
	v_mad_i64_i32 v[20:21], s[6:7], v20, s4, v[18:19]
	v_mad_i64_i32 v[30:31], s[6:7], v30, s4, v[18:19]
	v_mad_i64_i32 v[32:33], s[6:7], v32, s4, v[18:19]
	v_mad_i64_i32 v[34:35], s[6:7], v34, s4, v[18:19]
	v_mad_i64_i32 v[36:37], s[6:7], v36, s4, v[18:19]
	v_mad_i64_i32 v[38:39], s[6:7], v38, s4, v[18:19]
	v_mad_i64_i32 v[40:41], s[6:7], v40, s4, v[18:19]
	v_mad_i64_i32 v[42:43], s[6:7], v42, s4, v[18:19]
	v_mad_i64_i32 v[44:45], s[6:7], v44, s4, v[18:19]
	v_mad_i64_i32 v[46:47], s[6:7], v46, s4, v[18:19]
	v_mad_i64_i32 v[48:49], s[6:7], v48, s4, v[18:19]
	v_mad_i64_i32 v[50:51], s[6:7], v50, s4, v[18:19]
	v_mad_i64_i32 v[52:53], s[6:7], v52, s4, v[18:19]
	v_mad_i64_i32 v[54:55], s[6:7], v54, s4, v[18:19]
	v_mad_i64_i32 v[56:57], s[6:7], v56, s4, v[18:19]
	v_mad_i64_i32 v[22:23], s[6:7], v22, s4, v[18:19]
	v_mad_i64_i32 v[24:25], s[6:7], v24, s4, v[18:19]
	v_mad_i64_i32 v[26:27], s[6:7], v26, s4, v[18:19]
	v_mad_i64_i32 v[28:29], s[6:7], v28, s4, v[18:19]
	v_mad_i64_i32 v[58:59], s[6:7], v58, s4, v[18:19]
	v_mad_i64_i32 v[60:61], s[6:7], v60, s4, v[18:19]
	v_mad_i64_i32 v[62:63], s[6:7], v62, s4, v[18:19]
	v_mad_i64_i32 v[64:65], s[6:7], v64, s4, v[18:19]
	v_mad_i64_i32 v[66:67], s[6:7], v66, s4, v[18:19]
	v_mad_i64_i32 v[68:69], s[6:7], v68, s4, v[18:19]
	v_mad_i64_i32 v[70:71], s[6:7], v70, s4, v[18:19]
	v_mad_i64_i32 v[72:73], s[6:7], v72, s4, v[18:19]
	v_mad_i64_i32 v[74:75], s[6:7], v74, s4, v[18:19]
	v_mad_i64_i32 v[76:77], s[6:7], v76, s4, v[18:19]
	v_mad_i64_i32 v[78:79], s[6:7], v78, s4, v[18:19]
	v_mad_i64_i32 v[80:81], s[6:7], v80, s4, v[18:19]
	v_mad_i64_i32 v[18:19], s[6:7], v82, s4, v[18:19]
	global_load_dword v82, v[20:21], off nt
	global_load_dword v83, v[22:23], off nt
	global_load_dword v84, v[24:25], off nt
	global_load_dword v85, v[26:27], off nt
	global_load_dword v86, v[28:29], off nt
	s_nop 0
	global_load_dword v30, v[30:31], off nt
	s_nop 0
	global_load_dword v31, v[32:33], off nt
	s_nop 0
	global_load_dword v32, v[34:35], off nt
	global_load_dword v33, v[36:37], off nt
	s_nop 0
	global_load_dword v34, v[38:39], off nt
	global_load_dword v35, v[40:41], off nt
	global_load_dword v36, v[42:43], off nt
	global_load_dword v37, v[44:45], off nt
	s_nop 0
	global_load_dword v38, v[46:47], off nt
	global_load_dword v39, v[48:49], off nt
	global_load_dword v40, v[50:51], off nt
	global_load_dword v41, v[52:53], off nt
	global_load_dword v42, v[54:55], off nt
	global_load_dword v43, v[56:57], off nt
	global_load_dword v44, v[58:59], off nt
	global_load_dword v45, v[60:61], off nt
	global_load_dword v46, v[62:63], off nt
	global_load_dword v47, v[64:65], off nt
	global_load_dword v48, v[66:67], off nt
	global_load_dword v49, v[68:69], off nt
	global_load_dword v50, v[70:71], off nt
	global_load_dword v51, v[72:73], off nt
	global_load_dword v52, v[74:75], off nt
	global_load_dword v53, v[76:77], off nt
	global_load_dword v54, v[78:79], off nt
	global_load_dword v55, v[80:81], off nt
	global_load_dword v56, v[18:19], off nt
	v_or_b32_e32 v18, s2, v5
	v_or_b32_e32 v20, s2, v7
	s_ashr_i32 s1, s0, 31
	v_ashrrev_i32_e32 v19, 31, v18
	s_waitcnt vmcnt(30)
	ds_write2_b32 v10, v82, v83 offset1:66
	s_waitcnt vmcnt(28)
	ds_write2_b32 v10, v84, v85 offset0:132 offset1:198
	s_waitcnt vmcnt(26)
	ds_write2_b32 v11, v86, v30 offset0:8 offset1:74
	s_waitcnt vmcnt(24)
	ds_write2_b32 v11, v31, v32 offset0:140 offset1:206
	s_waitcnt vmcnt(22)
	ds_write2_b32 v12, v33, v34 offset0:16 offset1:82
	s_waitcnt vmcnt(20)
	ds_write2_b32 v12, v35, v36 offset0:148 offset1:214
	s_waitcnt vmcnt(18)
	ds_write2_b32 v13, v37, v38 offset0:24 offset1:90
	s_waitcnt vmcnt(16)
	ds_write2_b32 v13, v39, v40 offset0:156 offset1:222
	s_waitcnt vmcnt(14)
	ds_write2_b32 v14, v41, v42 offset0:32 offset1:98
	s_waitcnt vmcnt(12)
	ds_write2_b32 v14, v43, v44 offset0:164 offset1:230
	s_waitcnt vmcnt(10)
	ds_write2_b32 v15, v45, v46 offset0:40 offset1:106
	s_waitcnt vmcnt(8)
	ds_write2_b32 v15, v47, v48 offset0:172 offset1:238
	s_waitcnt vmcnt(6)
	ds_write2_b32 v16, v49, v50 offset0:48 offset1:114
	s_waitcnt vmcnt(4)
	ds_write2_b32 v16, v51, v52 offset0:180 offset1:246
	s_waitcnt vmcnt(2)
	ds_write2_b32 v17, v53, v54 offset0:56 offset1:122
	s_waitcnt vmcnt(0)
	ds_write2_b32 v17, v55, v56 offset0:188 offset1:254
	v_ashrrev_i32_e32 v21, 31, v20
	v_lshl_add_u64 v[24:25], s[0:1], 1, v[2:3]
	v_lshlrev_b64 v[18:19], 12, v[18:19]
	s_waitcnt lgkmcnt(0)
	v_lshlrev_b64 v[20:21], 12, v[20:21]
	v_lshl_add_u64 v[26:27], v[24:25], 0, v[18:19]
	ds_read2_b32 v[18:19], v6 offset1:33
	v_lshl_add_u64 v[28:29], v[24:25], 0, v[20:21]
	s_waitcnt lgkmcnt(0)
	v_cvt_pk_bf16_f32 v18, v18, v19
	ds_read2_b32 v[20:21], v6 offset0:66 offset1:99
	s_waitcnt lgkmcnt(0)
	v_cvt_pk_bf16_f32 v19, v20, v21
	ds_read2_b32 v[20:21], v6 offset0:132 offset1:165
	s_waitcnt lgkmcnt(0)
	v_cvt_pk_bf16_f32 v20, v20, v21
	ds_read2_b32 v[30:31], v6 offset0:198 offset1:231
	s_waitcnt lgkmcnt(0)
	v_cvt_pk_bf16_f32 v21, v30, v31
	ds_read2_b32 v[30:31], v6 offset0:8 offset1:41
	global_store_dwordx4 v[26:27], v[18:21], off
	v_or_b32_e32 v22, s2, v8
	v_ashrrev_i32_e32 v23, 31, v22
	s_waitcnt lgkmcnt(0)
	v_cvt_pk_bf16_f32 v18, v30, v31
	ds_read2_b32 v[20:21], v6 offset0:74 offset1:107
	s_waitcnt lgkmcnt(0)
	v_cvt_pk_bf16_f32 v19, v20, v21
	ds_read2_b32 v[20:21], v6 offset0:140 offset1:173
	s_waitcnt lgkmcnt(0)
	v_cvt_pk_bf16_f32 v20, v20, v21
	ds_read2_b32 v[26:27], v6 offset0:206 offset1:239
	s_waitcnt lgkmcnt(0)
	v_cvt_pk_bf16_f32 v21, v26, v27
	ds_read2_b32 v[26:27], v6 offset0:16 offset1:49
	global_store_dwordx4 v[28:29], v[18:21], off
	v_lshlrev_b64 v[22:23], 12, v[22:23]
	v_lshl_add_u64 v[22:23], v[24:25], 0, v[22:23]
	s_waitcnt lgkmcnt(0)
	v_cvt_pk_bf16_f32 v18, v26, v27
	ds_read2_b32 v[20:21], v6 offset0:82 offset1:115
	s_waitcnt lgkmcnt(0)
	v_cvt_pk_bf16_f32 v19, v20, v21
	ds_read2_b32 v[20:21], v6 offset0:148 offset1:181
	s_waitcnt lgkmcnt(0)
	v_cvt_pk_bf16_f32 v20, v20, v21
	ds_read2_b32 v[26:27], v6 offset0:214 offset1:247
	s_waitcnt lgkmcnt(0)
	v_cvt_pk_bf16_f32 v21, v26, v27
	ds_read2_b32 v[26:27], v6 offset0:24 offset1:57
	global_store_dwordx4 v[22:23], v[18:21], off
	s_add_i32 s0, s5, 0x400
	s_cmp_lt_i32 s0, s93
	s_waitcnt lgkmcnt(0)
	v_cvt_pk_bf16_f32 v18, v26, v27
	v_or_b32_e32 v26, s2, v9
	v_ashrrev_i32_e32 v27, 31, v26
	ds_read2_b32 v[20:21], v6 offset0:90 offset1:123
	v_lshlrev_b64 v[26:27], 12, v[26:27]
	s_waitcnt lgkmcnt(0)
	v_cvt_pk_bf16_f32 v19, v20, v21
	ds_read2_b32 v[20:21], v6 offset0:156 offset1:189
	v_lshl_add_u64 v[24:25], v[24:25], 0, v[26:27]
	s_waitcnt lgkmcnt(0)
	v_cvt_pk_bf16_f32 v20, v20, v21
	ds_read2_b32 v[22:23], v6 offset0:222 offset1:255
	s_waitcnt lgkmcnt(0)
	v_cvt_pk_bf16_f32 v21, v22, v23
	global_store_dwordx4 v[24:25], v[18:21], off
	s_waitcnt lgkmcnt(0)
	s_mov_b32 s5, s0
	s_cbranch_scc1 .LBB0_538
